# N2 norm loop: all four row loads issued up front (one round trip per row instead of two), counted vmcnt
# speedup vs baseline: 1.0061x; 1.0061x over previous
.LBB0_79:
	global_load_dwordx4 v[62:65], v[50:51], off offset:-3072
	global_load_dwordx4 v[66:69], v[50:51], off offset:-2048
	global_load_dwordx4 v[84:87], v[50:51], off offset:-1024
	global_load_dwordx4 v[80:83], v[50:51], off
	v_readlane_b32 s12, v252, 0
	v_readlane_b32 s13, v252, 1
	v_readlane_b32 s14, v252, 2
	v_readlane_b32 s15, v252, 3
	s_add_i32 s0, s0, 1
	s_cmp_ge_i32 s0, s2
	s_waitcnt vmcnt(2)
	v_pk_mul_f32 v[34:35], v[64:65], v[64:65]
	v_pk_mul_f32 v[36:37], v[62:63], v[62:63]
	s_nop 0
	v_pk_mov_b32 v[38:39], v[36:37], v[34:35] op_sel:[1,0]
	v_mov_b32_e32 v37, v35
	v_pk_add_f32 v[70:71], v[38:39], v[36:37]
	v_pk_mul_f32 v[34:35], v[68:69], v[68:69]
	v_pk_mul_f32 v[36:37], v[66:67], v[66:67]
	v_pk_add_f32 v[70:71], v[70:71], v[70:71] op_sel:[0,1] op_sel_hi:[1,0]
	v_pk_mov_b32 v[38:39], v[36:37], v[34:35] op_sel:[1,0]
	v_mov_b32_e32 v37, v35
	v_pk_add_f32 v[72:73], v[38:39], v[36:37]
	v_pk_add_f32 v[72:73], v[72:73], v[72:73] op_sel:[0,1] op_sel_hi:[1,0]
	v_lshl_add_u64 v[50:51], v[50:51], 0, s[20:21]
	s_waitcnt vmcnt(0)
	v_mul_f32_e32 v1, v80, v80
	v_mul_f32_e32 v61, v81, v81
	v_mov_b32_e32 v71, v1
	v_mov_b32_e32 v73, v61
	v_pk_add_f32 v[70:71], v[70:71], v[72:73]
	v_mul_f32_e32 v72, v85, v85
	v_mul_f32_e32 v74, v82, v82
	v_pk_fma_f32 v[72:73], v[84:85], v[84:85], v[72:73] op_sel_hi:[1,1,0]
	v_mul_f32_e32 v76, v83, v83
	v_mov_b32_e32 v73, v74
	v_mul_f32_e32 v74, v87, v87
	v_pk_fma_f32 v[74:75], v[86:87], v[86:87], v[74:75] op_sel_hi:[1,1,0]
	s_nop 0
	v_mov_b32_e32 v75, v76
	v_pk_add_f32 v[72:73], v[72:73], v[74:75]
	s_nop 0
	v_pk_add_f32 v[70:71], v[70:71], v[72:73]
	s_nop 0
	v_add_f32_e32 v1, v70, v71
	ds_bpermute_b32 v61, v54, v1
	s_waitcnt lgkmcnt(0)
	v_add_f32_e32 v1, v1, v61
	ds_bpermute_b32 v61, v55, v1
	s_waitcnt lgkmcnt(0)
	v_add_f32_e32 v1, v1, v61
	ds_bpermute_b32 v61, v56, v1
	s_waitcnt lgkmcnt(0)
	v_add_f32_e32 v1, v1, v61
	ds_bpermute_b32 v61, v57, v1
	s_waitcnt lgkmcnt(0)
	v_add_f32_e32 v1, v1, v61
	ds_bpermute_b32 v61, v58, v1
	s_waitcnt lgkmcnt(0)
	v_add_f32_e32 v1, v1, v61
	ds_bpermute_b32 v61, v59, v1
	s_waitcnt lgkmcnt(0)
	v_add_f32_e32 v1, v1, v61
	v_fmamk_f32 v1, v1, 0x3a800000, v201
	v_rsq_f32_e32 v70, v1
	v_add_u32_e32 v1, 0xfffffa00, v60
	v_pk_mul_f32 v[62:63], v[62:63], v[70:71] op_sel_hi:[1,0]
	v_pk_mul_f32 v[64:65], v[64:65], v[70:71] op_sel_hi:[1,0]
	v_pk_fma_f32 v[62:63], v[2:3], v[62:63], v[18:19]
	v_pk_fma_f32 v[64:65], v[4:5], v[64:65], v[20:21]
	v_cvt_pk_bf16_f32 v62, v62, v63
	v_cvt_pk_bf16_f32 v63, v64, v65
	buffer_store_dwordx2 v[62:63], v1, s[12:15], 0 offen sc1
	v_pk_mul_f32 v[62:63], v[66:67], v[70:71] op_sel_hi:[1,0]
	v_pk_mul_f32 v[64:65], v[68:69], v[70:71] op_sel_hi:[1,0]
	v_pk_fma_f32 v[62:63], v[6:7], v[62:63], v[22:23]
	v_pk_fma_f32 v[64:65], v[8:9], v[64:65], v[24:25]
	v_pk_mul_f32 v[84:85], v[84:85], v[70:71] op_sel_hi:[1,0]
	v_pk_mul_f32 v[86:87], v[86:87], v[70:71] op_sel_hi:[1,0]
	v_pk_mul_f32 v[80:81], v[80:81], v[70:71] op_sel_hi:[1,0]
	v_pk_mul_f32 v[82:83], v[82:83], v[70:71] op_sel_hi:[1,0]
	v_cvt_pk_bf16_f32 v62, v62, v63
	v_cvt_pk_bf16_f32 v63, v64, v65
	v_add_u32_e32 v1, 0xfffffc00, v60
	v_pk_fma_f32 v[86:87], v[12:13], v[86:87], v[28:29]
	v_pk_fma_f32 v[84:85], v[10:11], v[84:85], v[26:27]
	v_pk_fma_f32 v[82:83], v[16:17], v[82:83], v[32:33]
	v_pk_fma_f32 v[80:81], v[14:15], v[80:81], v[30:31]
	buffer_store_dwordx2 v[62:63], v1, s[12:15], 0 offen sc1
	v_cvt_pk_bf16_f32 v84, v84, v85
	v_cvt_pk_bf16_f32 v85, v86, v87
	v_add_u32_e32 v1, 0xfffffe00, v60
	v_cvt_pk_bf16_f32 v80, v80, v81
	v_cvt_pk_bf16_f32 v81, v82, v83
	buffer_store_dwordx2 v[84:85], v1, s[12:15], 0 offen sc1
	buffer_store_dwordx2 v[80:81], v60, s[12:15], 0 offen sc1
	v_add_u32_e32 v60, 0x800, v60
	s_cbranch_scc1 .LBB0_82
